# cmask rewrite + wave-uniform skip when the whole tile is visible to the wave
# speedup vs baseline: 1.0015x; 1.0015x over previous
;   #define RESC() do{ if(resc){ asm volatile("s_waitcnt lgkmcnt(0)":::"memory"); \
;       _Pragma("unroll") for(int d_=0;d_<2;++d_) _Pragma("unroll") for(int r=0;r<16;++r)o[d_][r]*=wsf[crow(r,hi)]; } }while(0)
;   #define ROT() do{sl_prev=sl_cur;sl_cur=sl_next;sl_next=(sl_next==(NSLOT-1)*SLOTB)?0:sl_next+SLOTB;}while(0)
;   #define ENDW(tt) do{ if((tt)+3<NT){WAIT_BAR(2);} else if((tt)+2<NT){WAIT_BAR(1);} else {WAIT_BAR(0);} }while(0)
; __device__ __forceinline__ void cmask(f32x16&p0,f32x16&p1,int jb,int qrel,int hi){
;   const float NEG=-INFINITY; int kb=64*jb+4*hi;
;   #pragma unroll
;   for(int r=0;r<16;++r){int kv=kb+(r&3)+8*(r>>2); if(kv>qrel)p0[r]=NEG; if(kv+32>qrel)p1[r]=NEG;}
; }
; template<int THRL,int MODE,int DM,bool DRY=false> __device__ __forceinline__ void attn_unit(int b,int h,int qb,const bf16*Q,const bf16*__restrict__ K,const bf16*__restrict__ V,bf16*O,const bf16*__restrict__ Z,const float*__restrict__ XP,const int*__restrict__ TS,volatile unsigned*lw,unsigned nxt,cha ...
;     ...
;   for(;t+1<NT;t+=2){
;     STEP(pB0,pB1,pA0,pA1,t,(t+3<NT),(t+1<NT),(t+1<NT));       ENDW(t);   RESC(); ROT();
;     STEP(pA0,pA1,pB0,pB1,t+1,(t+4<NT),(t+2<NT),(t+2<NT));     ENDW(t+1); RESC(); ROT();
.LBB0_923:
	s_add_i32 s19, s75, s18
	s_add_i32 s10, s19, 4
	s_cmp_lt_i32 s10, 0
	s_cbranch_scc1 .LBB0_925
	v_sub_u32_e32 v76, v246, v81
	v_cmp_gt_i32_e32 vcc, 59, v76
	s_cbranch_vccz .LBB0_925
	v_cmp_le_i32_e64 vcc, 32, v76
	v_cmp_le_i32_e64 s[98:99], 1, v76
	v_cmp_le_i32_e64 s[100:101], 0, v76
	v_cndmask_b32_e64 v112, v234, v112, vcc
	v_cmp_le_i32_e64 vcc, 33, v76
	v_cndmask_b32_e64 v129, v234, v129, s[98:99]
	v_cmp_le_i32_e64 s[98:99], 2, v76
	v_cndmask_b32_e64 v128, v234, v128, s[100:101]
	v_cmp_le_i32_e64 s[100:101], 34, v76
	v_cndmask_b32_e64 v113, v234, v113, vcc
	v_cmp_le_i32_e64 vcc, 3, v76
	v_cndmask_b32_e64 v130, v234, v130, s[98:99]
	v_cmp_le_i32_e64 s[98:99], 35, v76
	v_cndmask_b32_e64 v114, v234, v114, s[100:101]
	v_cmp_le_i32_e64 s[100:101], 8, v76
	v_cndmask_b32_e64 v131, v234, v131, vcc
	v_cmp_le_i32_e64 vcc, 40, v76
	v_cndmask_b32_e64 v115, v234, v115, s[98:99]
	v_cmp_le_i32_e64 s[98:99], 9, v76
	v_cndmask_b32_e64 v132, v234, v132, s[100:101]
	v_cmp_le_i32_e64 s[100:101], 41, v76
	v_cndmask_b32_e64 v116, v234, v116, vcc
	v_cmp_le_i32_e64 vcc, 10, v76
	v_cndmask_b32_e64 v133, v234, v133, s[98:99]
	v_cmp_le_i32_e64 s[98:99], 42, v76
	v_cndmask_b32_e64 v117, v234, v117, s[100:101]
	v_cmp_le_i32_e64 s[100:101], 11, v76
	v_cndmask_b32_e64 v134, v234, v134, vcc
	v_cmp_le_i32_e64 vcc, 43, v76
	v_cndmask_b32_e64 v118, v234, v118, s[98:99]
	v_cmp_le_i32_e64 s[98:99], 16, v76
	v_cndmask_b32_e64 v135, v234, v135, s[100:101]
	v_cmp_le_i32_e64 s[100:101], 48, v76
	v_cndmask_b32_e64 v119, v234, v119, vcc
	v_cmp_le_i32_e64 vcc, 17, v76
	v_cndmask_b32_e64 v136, v234, v136, s[98:99]
	v_cmp_le_i32_e64 s[98:99], 49, v76
	v_cndmask_b32_e64 v120, v234, v120, s[100:101]
	v_cmp_le_i32_e64 s[100:101], 18, v76
	v_cndmask_b32_e64 v137, v234, v137, vcc
	v_cmp_le_i32_e64 vcc, 50, v76
	v_cndmask_b32_e64 v121, v234, v121, s[98:99]
	v_cmp_le_i32_e64 s[98:99], 19, v76
	v_cndmask_b32_e64 v138, v234, v138, s[100:101]
	v_cmp_le_i32_e64 s[100:101], 51, v76
	v_cndmask_b32_e64 v122, v234, v122, vcc
	v_cmp_le_i32_e64 vcc, 24, v76
	v_cndmask_b32_e64 v139, v234, v139, s[98:99]
	v_cmp_le_i32_e64 s[98:99], 56, v76
	v_cndmask_b32_e64 v123, v234, v123, s[100:101]
	v_cmp_le_i32_e64 s[100:101], 25, v76
	v_cndmask_b32_e64 v140, v234, v140, vcc
	v_cmp_le_i32_e64 vcc, 57, v76
	v_cndmask_b32_e64 v124, v234, v124, s[98:99]
	v_cmp_le_i32_e64 s[98:99], 26, v76
	v_cndmask_b32_e64 v141, v234, v141, s[100:101]
	v_cmp_le_i32_e64 s[100:101], 58, v76
	v_cndmask_b32_e64 v125, v234, v125, vcc
	v_cmp_le_i32_e64 vcc, 27, v76
	v_cndmask_b32_e64 v142, v234, v142, s[98:99]
	v_cmp_le_i32_e64 s[98:99], 59, v76
	v_cndmask_b32_e64 v126, v234, v126, s[100:101]
	v_cndmask_b32_e64 v143, v234, v143, vcc
	v_cndmask_b32_e64 v127, v234, v127, s[98:99]

;   #define RESC() do{ if(resc){ asm volatile("s_waitcnt lgkmcnt(0)":::"memory"); \
;       _Pragma("unroll") for(int d_=0;d_<2;++d_) _Pragma("unroll") for(int r=0;r<16;++r)o[d_][r]*=wsf[crow(r,hi)]; } }while(0)
;   #define ROT() do{sl_prev=sl_cur;sl_cur=sl_next;sl_next=(sl_next==(NSLOT-1)*SLOTB)?0:sl_next+SLOTB;}while(0)
;   #define ENDW(tt) do{ if((tt)+3<NT){WAIT_BAR(2);} else if((tt)+2<NT){WAIT_BAR(1);} else {WAIT_BAR(0);} }while(0)
; __device__ __forceinline__ void cmask(f32x16&p0,f32x16&p1,int jb,int qrel,int hi){
;   const float NEG=-INFINITY; int kb=64*jb+4*hi;
;   #pragma unroll
;   for(int r=0;r<16;++r){int kv=kb+(r&3)+8*(r>>2); if(kv>qrel)p0[r]=NEG; if(kv+32>qrel)p1[r]=NEG;}
; }
; template<int THRL,int MODE,int DM,bool DRY=false> __device__ __forceinline__ void attn_unit(int b,int h,int qb,const bf16*Q,const bf16*__restrict__ K,const bf16*__restrict__ V,bf16*O,const bf16*__restrict__ Z,const float*__restrict__ XP,const int*__restrict__ TS,volatile unsigned*lw,unsigned nxt,cha ...
;     ...
;   for(;t+1<NT;t+=2){
;     STEP(pB0,pB1,pA0,pA1,t,(t+3<NT),(t+1<NT),(t+1<NT));       ENDW(t);   RESC(); ROT();
;     STEP(pA0,pA1,pB0,pB1,t+1,(t+4<NT),(t+2<NT),(t+2<NT));     ENDW(t+1); RESC(); ROT();
.LBB0_935:
	v_sub_u32_e32 v113, v246, v81
	v_subrev_u32_e32 v113, 64, v113
	v_cmp_gt_i32_e32 vcc, 59, v113
	s_cbranch_vccz .LBB0_936
	v_cmp_le_i32_e64 vcc, 32, v113
	v_cmp_le_i32_e64 s[98:99], 1, v113
	v_cmp_le_i32_e64 s[100:101], 0, v113
	v_cndmask_b32_e64 v64, v234, v64, vcc
	v_cmp_le_i32_e64 vcc, 33, v113
	v_cndmask_b32_e64 v97, v234, v97, s[98:99]
	v_cmp_le_i32_e64 s[98:99], 2, v113
	v_cndmask_b32_e64 v96, v234, v96, s[100:101]
	v_cmp_le_i32_e64 s[100:101], 34, v113
	v_cndmask_b32_e64 v65, v234, v65, vcc
	v_cmp_le_i32_e64 vcc, 3, v113
	v_cndmask_b32_e64 v98, v234, v98, s[98:99]
	v_cmp_le_i32_e64 s[98:99], 35, v113
	v_cndmask_b32_e64 v66, v234, v66, s[100:101]
	v_cmp_le_i32_e64 s[100:101], 8, v113
	v_cndmask_b32_e64 v99, v234, v99, vcc
	v_cmp_le_i32_e64 vcc, 40, v113
	v_cndmask_b32_e64 v67, v234, v67, s[98:99]
	v_cmp_le_i32_e64 s[98:99], 9, v113
	v_cndmask_b32_e64 v100, v234, v100, s[100:101]
	v_cmp_le_i32_e64 s[100:101], 41, v113
	v_cndmask_b32_e64 v68, v234, v68, vcc
	v_cmp_le_i32_e64 vcc, 10, v113
	v_cndmask_b32_e64 v101, v234, v101, s[98:99]
	v_cmp_le_i32_e64 s[98:99], 42, v113
	v_cndmask_b32_e64 v69, v234, v69, s[100:101]
	v_cmp_le_i32_e64 s[100:101], 11, v113
	v_cndmask_b32_e64 v102, v234, v102, vcc
	v_cmp_le_i32_e64 vcc, 43, v113
	v_cndmask_b32_e64 v70, v234, v70, s[98:99]
	v_cmp_le_i32_e64 s[98:99], 16, v113
	v_cndmask_b32_e64 v103, v234, v103, s[100:101]
	v_cmp_le_i32_e64 s[100:101], 48, v113
	v_cndmask_b32_e64 v71, v234, v71, vcc
	v_cmp_le_i32_e64 vcc, 17, v113
	v_cndmask_b32_e64 v104, v234, v104, s[98:99]
	v_cmp_le_i32_e64 s[98:99], 49, v113
	v_cndmask_b32_e64 v72, v234, v72, s[100:101]
	v_cmp_le_i32_e64 s[100:101], 18, v113
	v_cndmask_b32_e64 v105, v234, v105, vcc
	v_cmp_le_i32_e64 vcc, 50, v113
	v_cndmask_b32_e64 v73, v234, v73, s[98:99]
	v_cmp_le_i32_e64 s[98:99], 19, v113
	v_cndmask_b32_e64 v106, v234, v106, s[100:101]
	v_cmp_le_i32_e64 s[100:101], 51, v113
	v_cndmask_b32_e64 v74, v234, v74, vcc
	v_cmp_le_i32_e64 vcc, 24, v113
	v_cndmask_b32_e64 v107, v234, v107, s[98:99]
	v_cmp_le_i32_e64 s[98:99], 56, v113
	v_cndmask_b32_e64 v75, v234, v75, s[100:101]
	v_cmp_le_i32_e64 s[100:101], 25, v113
	v_cndmask_b32_e64 v108, v234, v108, vcc
	v_cmp_le_i32_e64 vcc, 57, v113
	v_cndmask_b32_e64 v76, v234, v76, s[98:99]
	v_cmp_le_i32_e64 s[98:99], 26, v113
	v_cndmask_b32_e64 v109, v234, v109, s[100:101]
	v_cmp_le_i32_e64 s[100:101], 58, v113
	v_cndmask_b32_e64 v77, v234, v77, vcc
	v_cmp_le_i32_e64 vcc, 27, v113
	v_cndmask_b32_e64 v110, v234, v110, s[98:99]
	v_cmp_le_i32_e64 s[98:99], 59, v113
	v_cndmask_b32_e64 v78, v234, v78, s[100:101]
	v_cndmask_b32_e64 v111, v234, v111, vcc
	v_cndmask_b32_e64 v79, v234, v79, s[98:99]

; __device__ __forceinline__ void cmask(f32x16&p0,f32x16&p1,int jb,int qrel,int hi){
;   const float NEG=-INFINITY; int kb=64*jb+4*hi;
;   #pragma unroll
;   for(int r=0;r<16;++r){int kv=kb+(r&3)+8*(r>>2); if(kv>qrel)p0[r]=NEG; if(kv+32>qrel)p1[r]=NEG;}
; }
.LBB0_1474:
	v_lshl_add_u64 v[200:201], v[198:199], 0, s[54:55]
	v_lshl_add_u64 v[32:33], v[200:201], 0, s[48:49]
	s_add_i32 s10, s66, s84
	s_mov_b32 s11, m0
	s_mov_b32 m0, s10
	s_nop 0
	global_load_lds_dwordx4 v[32:33], off
	s_mov_b32 m0, s11
	ds_read_b128 v[32:35], v192
	ds_read_b128 v[36:39], v192 offset:32
	ds_read_b128 v[40:43], v192 offset:128
	ds_read_b128 v[44:47], v192 offset:160
	ds_read_b128 v[48:51], v192 offset:64
	ds_read_b128 v[52:55], v192 offset:96
	ds_read_b128 v[128:131], v192 offset:192
	ds_read_b128 v[134:137], v192 offset:224
	s_waitcnt lgkmcnt(7)
	v_pk_add_f32 v[34:35], v[194:195], v[34:35] op_sel_hi:[0,1]
	s_waitcnt lgkmcnt(6)
	v_pk_add_f32 v[38:39], v[194:195], v[38:39] op_sel_hi:[0,1]
	s_waitcnt lgkmcnt(3)
	v_pk_add_f32 v[50:51], v[194:195], v[50:51] op_sel_hi:[0,1]
	s_waitcnt lgkmcnt(2)
	v_pk_add_f32 v[54:55], v[194:195], v[54:55] op_sel_hi:[0,1]
	v_pk_add_f32 v[32:33], v[194:195], v[32:33] op_sel_hi:[0,1]
	v_pk_add_f32 v[36:37], v[194:195], v[36:37] op_sel_hi:[0,1]
	v_pk_add_f32 v[48:49], v[194:195], v[48:49] op_sel_hi:[0,1]
	v_pk_add_f32 v[52:53], v[194:195], v[52:53] op_sel_hi:[0,1]
	s_add_i32 s63, s85, s62
	v_sub_f32_e32 v63, v95, v55
	v_sub_f32_e32 v62, v94, v54
	v_sub_f32_e32 v59, v91, v51
	v_sub_f32_e32 v58, v90, v50
	v_sub_f32_e32 v55, v87, v39
	v_sub_f32_e32 v54, v86, v38
	v_sub_f32_e32 v51, v83, v35
	v_sub_f32_e32 v50, v82, v34
	v_sub_f32_e32 v61, v93, v53
	v_sub_f32_e32 v60, v92, v52
	v_sub_f32_e32 v57, v89, v49
	v_sub_f32_e32 v56, v88, v48
	v_sub_f32_e32 v53, v85, v37
	v_sub_f32_e32 v52, v84, v36
	v_sub_f32_e32 v49, v81, v33
	v_sub_f32_e32 v48, v80, v32
	v_pk_add_f32 v[32:33], v[194:195], v[42:43] op_sel_hi:[0,1]
	v_pk_add_f32 v[34:35], v[194:195], v[46:47] op_sel_hi:[0,1]
	s_waitcnt lgkmcnt(1)
	v_pk_add_f32 v[36:37], v[194:195], v[130:131] op_sel_hi:[0,1]
	s_waitcnt lgkmcnt(0)
	v_pk_add_f32 v[38:39], v[194:195], v[136:137] op_sel_hi:[0,1]
	v_pk_add_f32 v[80:81], v[194:195], v[40:41] op_sel_hi:[0,1]
	v_pk_add_f32 v[82:83], v[194:195], v[44:45] op_sel_hi:[0,1]
	v_pk_add_f32 v[40:41], v[194:195], v[128:129] op_sel_hi:[0,1]
	v_pk_add_f32 v[44:45], v[194:195], v[134:135] op_sel_hi:[0,1]
	s_add_i32 s10, s63, 2
	v_sub_f32_e32 v47, v79, v39
	v_sub_f32_e32 v46, v78, v38
	v_sub_f32_e32 v43, v75, v37
	v_sub_f32_e32 v42, v74, v36
	v_sub_f32_e32 v39, v71, v35
	v_sub_f32_e32 v38, v70, v34
	v_sub_f32_e32 v35, v67, v33
	v_sub_f32_e32 v34, v66, v32
	v_sub_f32_e32 v45, v77, v45
	v_sub_f32_e32 v44, v76, v44
	v_sub_f32_e32 v41, v73, v41
	v_sub_f32_e32 v40, v72, v40
	v_sub_f32_e32 v37, v69, v83
	v_sub_f32_e32 v36, v68, v82
	v_sub_f32_e32 v33, v65, v81
	s_cmp_lt_i32 s10, 0
	v_sub_f32_e32 v32, v64, v80
	s_cbranch_scc1 .LBB0_1476
	v_sub_u32_e32 v64, v214, v224
	v_cmp_gt_i32_e32 vcc, 59, v64
	s_cbranch_vccz .LBB0_1476
	v_cmp_le_i32_e64 vcc, 32, v64
	v_cmp_le_i32_e64 s[98:99], 1, v64
	v_cmp_le_i32_e64 s[100:101], 0, v64
	v_cndmask_b32_e64 v32, v205, v32, vcc
	v_cmp_le_i32_e64 vcc, 33, v64
	v_cndmask_b32_e64 v49, v205, v49, s[98:99]
	v_cmp_le_i32_e64 s[98:99], 2, v64
	v_cndmask_b32_e64 v48, v205, v48, s[100:101]
	v_cmp_le_i32_e64 s[100:101], 34, v64
	v_cndmask_b32_e64 v33, v205, v33, vcc
	v_cmp_le_i32_e64 vcc, 3, v64
	v_cndmask_b32_e64 v50, v205, v50, s[98:99]
	v_cmp_le_i32_e64 s[98:99], 35, v64
	v_cndmask_b32_e64 v34, v205, v34, s[100:101]
	v_cmp_le_i32_e64 s[100:101], 8, v64
	v_cndmask_b32_e64 v51, v205, v51, vcc
	v_cmp_le_i32_e64 vcc, 40, v64
	v_cndmask_b32_e64 v35, v205, v35, s[98:99]
	v_cmp_le_i32_e64 s[98:99], 9, v64
	v_cndmask_b32_e64 v52, v205, v52, s[100:101]
	v_cmp_le_i32_e64 s[100:101], 41, v64
	v_cndmask_b32_e64 v36, v205, v36, vcc
	v_cmp_le_i32_e64 vcc, 10, v64
	v_cndmask_b32_e64 v53, v205, v53, s[98:99]
	v_cmp_le_i32_e64 s[98:99], 42, v64
	v_cndmask_b32_e64 v37, v205, v37, s[100:101]
	v_cmp_le_i32_e64 s[100:101], 11, v64
	v_cndmask_b32_e64 v54, v205, v54, vcc
	v_cmp_le_i32_e64 vcc, 43, v64
	v_cndmask_b32_e64 v38, v205, v38, s[98:99]
	v_cmp_le_i32_e64 s[98:99], 16, v64
	v_cndmask_b32_e64 v55, v205, v55, s[100:101]
	v_cmp_le_i32_e64 s[100:101], 48, v64
	v_cndmask_b32_e64 v39, v205, v39, vcc
	v_cmp_le_i32_e64 vcc, 17, v64
	v_cndmask_b32_e64 v56, v205, v56, s[98:99]
	v_cmp_le_i32_e64 s[98:99], 49, v64
	v_cndmask_b32_e64 v40, v205, v40, s[100:101]
	v_cmp_le_i32_e64 s[100:101], 18, v64
	v_cndmask_b32_e64 v57, v205, v57, vcc
	v_cmp_le_i32_e64 vcc, 50, v64
	v_cndmask_b32_e64 v41, v205, v41, s[98:99]
	v_cmp_le_i32_e64 s[98:99], 19, v64
	v_cndmask_b32_e64 v58, v205, v58, s[100:101]
	v_cmp_le_i32_e64 s[100:101], 51, v64
	v_cndmask_b32_e64 v42, v205, v42, vcc
	v_cmp_le_i32_e64 vcc, 24, v64
	v_cndmask_b32_e64 v59, v205, v59, s[98:99]
	v_cmp_le_i32_e64 s[98:99], 56, v64
	v_cndmask_b32_e64 v43, v205, v43, s[100:101]
	v_cmp_le_i32_e64 s[100:101], 25, v64
	v_cndmask_b32_e64 v60, v205, v60, vcc
	v_cmp_le_i32_e64 vcc, 57, v64
	v_cndmask_b32_e64 v44, v205, v44, s[98:99]
	v_cmp_le_i32_e64 s[98:99], 26, v64
	v_cndmask_b32_e64 v61, v205, v61, s[100:101]
	v_cmp_le_i32_e64 s[100:101], 58, v64
	v_cndmask_b32_e64 v45, v205, v45, vcc
	v_cmp_le_i32_e64 vcc, 27, v64
	v_cndmask_b32_e64 v62, v205, v62, s[98:99]
	v_cmp_le_i32_e64 s[98:99], 59, v64
	v_cndmask_b32_e64 v46, v205, v46, s[100:101]
	v_cndmask_b32_e64 v63, v205, v63, vcc
	v_cndmask_b32_e64 v47, v205, v47, s[98:99]

; __device__ __forceinline__ void cmask(f32x16&p0,f32x16&p1,int jb,int qrel,int hi){
;   const float NEG=-INFINITY; int kb=64*jb+4*hi;
;   #pragma unroll
;   for(int r=0;r<16;++r){int kv=kb+(r&3)+8*(r>>2); if(kv>qrel)p0[r]=NEG; if(kv+32>qrel)p1[r]=NEG;}
; }
.LBB0_1485:
	ds_read_b128 v[32:35], v192 offset:256
	ds_read_b128 v[36:39], v192 offset:288
	ds_read_b128 v[40:43], v192 offset:384
	ds_read_b128 v[44:47], v192 offset:416
	ds_read_b128 v[48:51], v192 offset:320
	ds_read_b128 v[52:55], v192 offset:352
	ds_read_b128 v[200:203], v192 offset:448
	ds_read_b128 v[228:231], v192 offset:480
	s_waitcnt lgkmcnt(7)
	v_pk_add_f32 v[34:35], v[194:195], v[34:35] op_sel_hi:[0,1]
	s_waitcnt lgkmcnt(6)
	v_pk_add_f32 v[38:39], v[194:195], v[38:39] op_sel_hi:[0,1]
	s_waitcnt lgkmcnt(3)
	v_pk_add_f32 v[50:51], v[194:195], v[50:51] op_sel_hi:[0,1]
	s_waitcnt lgkmcnt(2)
	v_pk_add_f32 v[54:55], v[194:195], v[54:55] op_sel_hi:[0,1]
	v_pk_add_f32 v[32:33], v[194:195], v[32:33] op_sel_hi:[0,1]
	v_pk_add_f32 v[36:37], v[194:195], v[36:37] op_sel_hi:[0,1]
	v_pk_add_f32 v[48:49], v[194:195], v[48:49] op_sel_hi:[0,1]
	v_pk_add_f32 v[52:53], v[194:195], v[52:53] op_sel_hi:[0,1]
	v_sub_f32_e32 v63, v95, v55
	v_sub_f32_e32 v62, v94, v54
	v_sub_f32_e32 v59, v91, v51
	v_sub_f32_e32 v58, v90, v50
	v_sub_f32_e32 v55, v87, v39
	v_sub_f32_e32 v54, v86, v38
	v_sub_f32_e32 v51, v83, v35
	v_sub_f32_e32 v50, v82, v34
	v_sub_f32_e32 v61, v93, v53
	v_sub_f32_e32 v60, v92, v52
	v_sub_f32_e32 v57, v89, v49
	v_sub_f32_e32 v56, v88, v48
	v_sub_f32_e32 v53, v85, v37
	v_sub_f32_e32 v52, v84, v36
	v_sub_f32_e32 v49, v81, v33
	v_sub_f32_e32 v48, v80, v32
	v_pk_add_f32 v[32:33], v[194:195], v[42:43] op_sel_hi:[0,1]
	v_pk_add_f32 v[34:35], v[194:195], v[46:47] op_sel_hi:[0,1]
	s_waitcnt lgkmcnt(1)
	v_pk_add_f32 v[36:37], v[194:195], v[202:203] op_sel_hi:[0,1]
	s_waitcnt lgkmcnt(0)
	v_pk_add_f32 v[38:39], v[194:195], v[230:231] op_sel_hi:[0,1]
	v_pk_add_f32 v[80:81], v[194:195], v[40:41] op_sel_hi:[0,1]
	v_pk_add_f32 v[82:83], v[194:195], v[44:45] op_sel_hi:[0,1]
	v_pk_add_f32 v[40:41], v[194:195], v[200:201] op_sel_hi:[0,1]
	v_pk_add_f32 v[44:45], v[194:195], v[228:229] op_sel_hi:[0,1]
	s_add_i32 s63, s63, 3
	v_sub_f32_e32 v47, v79, v39
	v_sub_f32_e32 v46, v78, v38
	v_sub_f32_e32 v43, v75, v37
	v_sub_f32_e32 v42, v74, v36
	v_sub_f32_e32 v39, v71, v35
	v_sub_f32_e32 v38, v70, v34
	v_sub_f32_e32 v35, v67, v33
	v_sub_f32_e32 v34, v66, v32
	v_sub_f32_e32 v45, v77, v45
	v_sub_f32_e32 v44, v76, v44
	v_sub_f32_e32 v41, v73, v41
	v_sub_f32_e32 v40, v72, v40
	v_sub_f32_e32 v37, v69, v83
	v_sub_f32_e32 v36, v68, v82
	v_sub_f32_e32 v33, v65, v81
	s_cmp_lt_i32 s63, 0
	v_sub_f32_e32 v32, v64, v80
	s_cbranch_scc1 .LBB0_1487
	v_sub_u32_e32 v65, v214, v224
	v_subrev_u32_e32 v65, 64, v65
	v_cmp_gt_i32_e32 vcc, 59, v65
	s_cbranch_vccz .LBB0_1487
	v_cmp_le_i32_e64 vcc, 32, v65
	v_cmp_le_i32_e64 s[98:99], 1, v65
	v_cmp_le_i32_e64 s[100:101], 0, v65
	v_cndmask_b32_e64 v32, v205, v32, vcc
	v_cmp_le_i32_e64 vcc, 33, v65
	v_cndmask_b32_e64 v49, v205, v49, s[98:99]
	v_cmp_le_i32_e64 s[98:99], 2, v65
	v_cndmask_b32_e64 v48, v205, v48, s[100:101]
	v_cmp_le_i32_e64 s[100:101], 34, v65
	v_cndmask_b32_e64 v33, v205, v33, vcc
	v_cmp_le_i32_e64 vcc, 3, v65
	v_cndmask_b32_e64 v50, v205, v50, s[98:99]
	v_cmp_le_i32_e64 s[98:99], 35, v65
	v_cndmask_b32_e64 v34, v205, v34, s[100:101]
	v_cmp_le_i32_e64 s[100:101], 8, v65
	v_cndmask_b32_e64 v51, v205, v51, vcc
	v_cmp_le_i32_e64 vcc, 40, v65
	v_cndmask_b32_e64 v35, v205, v35, s[98:99]
	v_cmp_le_i32_e64 s[98:99], 9, v65
	v_cndmask_b32_e64 v52, v205, v52, s[100:101]
	v_cmp_le_i32_e64 s[100:101], 41, v65
	v_cndmask_b32_e64 v36, v205, v36, vcc
	v_cmp_le_i32_e64 vcc, 10, v65
	v_cndmask_b32_e64 v53, v205, v53, s[98:99]
	v_cmp_le_i32_e64 s[98:99], 42, v65
	v_cndmask_b32_e64 v37, v205, v37, s[100:101]
	v_cmp_le_i32_e64 s[100:101], 11, v65
	v_cndmask_b32_e64 v54, v205, v54, vcc
	v_cmp_le_i32_e64 vcc, 43, v65
	v_cndmask_b32_e64 v38, v205, v38, s[98:99]
	v_cmp_le_i32_e64 s[98:99], 16, v65
	v_cndmask_b32_e64 v55, v205, v55, s[100:101]
	v_cmp_le_i32_e64 s[100:101], 48, v65
	v_cndmask_b32_e64 v39, v205, v39, vcc
	v_cmp_le_i32_e64 vcc, 17, v65
	v_cndmask_b32_e64 v56, v205, v56, s[98:99]
	v_cmp_le_i32_e64 s[98:99], 49, v65
	v_cndmask_b32_e64 v40, v205, v40, s[100:101]
	v_cmp_le_i32_e64 s[100:101], 18, v65
	v_cndmask_b32_e64 v57, v205, v57, vcc
	v_cmp_le_i32_e64 vcc, 50, v65
	v_cndmask_b32_e64 v41, v205, v41, s[98:99]
	v_cmp_le_i32_e64 s[98:99], 19, v65
	v_cndmask_b32_e64 v58, v205, v58, s[100:101]
	v_cmp_le_i32_e64 s[100:101], 51, v65
	v_cndmask_b32_e64 v42, v205, v42, vcc
	v_cmp_le_i32_e64 vcc, 24, v65
	v_cndmask_b32_e64 v59, v205, v59, s[98:99]
	v_cmp_le_i32_e64 s[98:99], 56, v65
	v_cndmask_b32_e64 v43, v205, v43, s[100:101]
	v_cmp_le_i32_e64 s[100:101], 25, v65
	v_cndmask_b32_e64 v60, v205, v60, vcc
	v_cmp_le_i32_e64 vcc, 57, v65
	v_cndmask_b32_e64 v44, v205, v44, s[98:99]
	v_cmp_le_i32_e64 s[98:99], 26, v65
	v_cndmask_b32_e64 v61, v205, v61, s[100:101]
	v_cmp_le_i32_e64 s[100:101], 58, v65
	v_cndmask_b32_e64 v45, v205, v45, vcc
	v_cmp_le_i32_e64 vcc, 27, v65
	v_cndmask_b32_e64 v62, v205, v62, s[98:99]
	v_cmp_le_i32_e64 s[98:99], 59, v65
	v_cndmask_b32_e64 v46, v205, v46, s[100:101]
	v_cndmask_b32_e64 v63, v205, v63, vcc
	v_cndmask_b32_e64 v47, v205, v47, s[98:99]
